# v098 + s_setprio 3 for the P4 scan compute waves (over helper waves sharing their SIMD), placement matched
# speedup vs baseline: 1.0171x; 1.0088x over previous
; #define SC_LOAD(tc) do { const size_t o_ = base + (size_t)(tc) * 1024 + q * 4; ld_dec = *(const f32x4*)(DEC + o_); ld_kk = *(const u32x2*)(KKn + o_); ld_bb = *(const u32x2*)(BB + o_); \
;             ld_kp = *(const u32x2*)(KP + o_); ld_rr = *(const u32x2*)(RR + o_); ld_vv = *(const unsigned*)(VV + base + (size_t)(tc) * 1024 + half * 32 + q * 2); } while (0)
; __global__ void __launch_bounds__(NT, 2) mk_fwd(Args args) {
;     ...
;         for (int task_ = bx; task_ < 256 * RMUL(4); task_ += G) {
;             const int tb_ = task_ & 255; const int task = ((tb_ >> 4) << 4) | ((tb_ & 7) << 1) | ((tb_ >> 3) & 1); const int bh = task >> 1, half = task & 1, b = bh >> 4, h = bh & 15;
;             const int stp = tid >> 4, q = tid & 15;
;             const size_t base = ((size_t)b * SEQ + stp) * 1024 + h * 64;
;             f32x4 ld_dec; u32x2 ld_kk, ld_bb, ld_kp, ld_rr; unsigned ld_vv;
;     ...
;             __syncthreads();
;             SC_LOAD(0); SC_STORE();
;             __syncthreads();
;             f32x4 S = (f32x4){0.f, 0.f, 0.f, 0.f};
;             const int row = wave * 4 + (lane >> 4), kl = lane & 15;
.Lp4_task:
	s_and_b32 s3, s48, 0xf0
	s_and_b32 s6, s48, 7
	s_lshl_b32 s6, s6, 1
	s_or_b32 s3, s3, s6
	s_bfe_u32 s6, s48, 0x10003
	s_or_b32 s3, s3, s6
	s_and_b32 s33, s3, 1
	s_lshr_b32 s6, s3, 1
	s_and_b32 s7, s6, 15
	s_lshr_b32 s6, s6, 4
	s_lshl_b32 s6, s6, 21
	s_lshl_b32 s7, s7, 6
	s_or_b32 s6, s6, s7
	s_lshl_b32 s7, s6, 1
	s_lshl_b32 s8, s6, 2
	s_add_u32 s38, s90, s8
	s_addc_u32 s39, s91, 0
	s_add_u32 s40, s30, s7
	s_addc_u32 s41, s31, 0
	s_add_u32 s42, s34, s7
	s_addc_u32 s43, s35, 0
	s_add_u32 s44, s96, s7
	s_addc_u32 s45, s97, 0
	s_add_u32 s46, s28, s7
	s_addc_u32 s47, s29, 0
	s_lshl_b32 s9, s33, 6
	s_add_u32 s9, s9, s7
	s_add_u32 s52, s24, s9
	s_addc_u32 s53, s25, 0
	s_lshl_b32 s9, s33, 7
	s_add_u32 s9, s9, s8
	s_add_u32 s54, s20, s9
	s_addc_u32 s55, s21, 0
	s_waitcnt vmcnt(0) lgkmcnt(0)
	s_barrier
	s_cmp_gt_u32 s85, 3
	s_cbranch_scc1 .Lp4_helper
	v_and_b32_e32 v54, 15, v128
	v_lshrrev_b32_e32 v55, 4, v128
	v_lshl_or_b32 v55, s85, 2, v55
	v_lshlrev_b32_e32 v80, 4, v54
	v_lshlrev_b32_e32 v81, 3, v55
	v_add_u32_e32 v81, 0x5000, v81
	v_mul_u32_u24_e32 v82, 0x90, v55
	v_lshl_add_u32 v82, v54, 3, v82
	v_add_u32_e32 v82, 0xb000, v82
	v_mov_b32_e32 v72, 0
	v_mov_b32_e32 v73, 0
	v_mov_b32_e32 v74, 0
	v_mov_b32_e32 v75, 0
	v_mov_b32_e32 v76, 0
	v_mov_b32_e32 v77, 0
	v_mov_b32_e32 v78, 0
	v_mov_b32_e32 v79, 0
	s_movk_i32 s10, 0x80
	s_barrier
	s_setprio 3
	s_nop 0
	s_nop 0
	s_nop 0

; __global__ void __launch_bounds__(NT, 2) mk_fwd(Args args) {
;     ...
;         for (int task_ = bx; task_ < 256 * RMUL(4); task_ += G) {
.Lp4_taskend:
	s_setprio 0
	s_add_i32 s48, s48, s84
	s_cmpk_gt_i32 s48, 0xff
	s_cbranch_scc0 .Lp4_task
	s_nop 0
	s_nop 0
	s_nop 0
	s_nop 0
	s_nop 0
	s_nop 0
	s_nop 0
	s_nop 0
	s_nop 0
	s_nop 0
	s_nop 0
	s_nop 0
	s_nop 0
	s_nop 0
	s_nop 0
